# v086 with RG-LRU scan LDS prefetch distance 7 steps instead of 5
# speedup vs baseline: 1.0084x; 1.0084x over previous
; #define LAS __attribute__((address_space(3)))
; DI unsigned pk2(float a, float b) { f32x2 v = {a, b}; bf2_t r = __builtin_convertvector(v, bf2_t); return __builtin_bit_cast(unsigned, r); }
; DI void phase_rglru(const Params& p, unsigned char* shm) {
;     ...
;             if (tid < 192) {
; #pragma unroll 8
;                 for (int r = 0; r < 64; ++r) {
;                     const float om = __uint_as_float((unsigned)*(const LAS bf16_t*)(lds + LAo + r * TR + tid * 2) << 16);
;                     const float bt = __uint_as_float((unsigned)*(const LAS bf16_t*)(lds + BTo + r * TR + tid * 2) << 16);
;                     const float g = __uint_as_float((unsigned)*(const LAS bf16_t*)(lds + GT + r * TR + tid * 2) << 16);
;                     hst = (hst - om * hst) + bt;
;                     *(LAS bf16_t*)(lds + GT + r * TR + tid * 2) = (bf16_t)(pk2(hst * g, 0.f) & 0xffffu);
;                 }
.LBB0_851:
	s_andn2_saveexec_b64 s[2:3], s[2:3]
	s_cbranch_execz .LBB0_842
	v_mov_b32_e32 v126, 0
	v_mov_b32_e32 v127, 0
	v_mov_b32_e32 v128, 0
	v_mov_b32_e32 v129, 0
	v_mov_b32_e32 v130, 0
	v_mov_b32_e32 v131, 0
	v_mov_b32_e32 v132, 0
	v_mov_b32_e32 v133, 0
	v_mov_b32_e32 v134, 0
	v_mov_b32_e32 v135, 0
	v_mov_b32_e32 v136, 0
	v_mov_b32_e32 v137, 0
	v_mov_b32_e32 v138, 0
	v_mov_b32_e32 v139, 0
	v_mov_b32_e32 v140, 0
	v_mov_b32_e32 v141, 0
	v_mov_b32_e32 v142, 0
	v_mov_b32_e32 v143, 0
	v_mov_b32_e32 v144, 0
	v_mov_b32_e32 v145, 0
	v_mov_b32_e32 v146, 0
	v_mov_b32_e32 v147, 0
	v_mov_b32_e32 v148, 0
	v_mov_b32_e32 v149, 0
	v_add_u32_e32 v121, 0x13100, v176
	v_add_u32_e32 v122, 0x19500, v176
	v_add_u32_e32 v123, 0xcd00, v176
	v_lshlrev_b32_e32 v124, 1, v176
	v_add_u32_e32 v124, 0x6900, v124
	ds_read_u16_d16_hi v126, v121
	ds_read_u16_d16_hi v134, v122
	ds_read_u16_d16_hi v142, v123
	ds_read_u16_d16_hi v127, v121 offset:400
	ds_read_u16_d16_hi v135, v122 offset:400
	ds_read_u16_d16_hi v143, v123 offset:400
	ds_read_u16_d16_hi v128, v121 offset:800
	ds_read_u16_d16_hi v136, v122 offset:800
	ds_read_u16_d16_hi v144, v123 offset:800
	ds_read_u16_d16_hi v129, v121 offset:1200
	ds_read_u16_d16_hi v137, v122 offset:1200
	ds_read_u16_d16_hi v145, v123 offset:1200
	ds_read_u16_d16_hi v130, v121 offset:1600
	ds_read_u16_d16_hi v138, v122 offset:1600
	ds_read_u16_d16_hi v146, v123 offset:1600
	ds_read_u16_d16_hi v131, v121 offset:2000
	ds_read_u16_d16_hi v139, v122 offset:2000
	ds_read_u16_d16_hi v147, v123 offset:2000
	ds_read_u16_d16_hi v132, v121 offset:2400
	ds_read_u16_d16_hi v140, v122 offset:2400
	ds_read_u16_d16_hi v148, v123 offset:2400
	s_waitcnt lgkmcnt(15)
	v_fma_f32 v150, -v152, v126, v152
	v_add_f32_e32 v152, v150, v134
	v_mul_f32_e32 v170, v152, v142
	ds_read_u16_d16_hi v133, v121 offset:2800
	ds_read_u16_d16_hi v141, v122 offset:2800
	ds_read_u16_d16_hi v149, v123 offset:2800
	s_waitcnt lgkmcnt(15)
	v_fma_f32 v150, -v152, v127, v152
	v_add_f32_e32 v152, v150, v135
	v_mul_f32_e32 v171, v152, v143
	ds_read_u16_d16_hi v126, v121 offset:3200
	ds_read_u16_d16_hi v134, v122 offset:3200
	ds_read_u16_d16_hi v142, v123 offset:3200
	v_cvt_pk_bf16_f32 v151, v170, v171
	ds_write_b32 v124, v151
	s_waitcnt lgkmcnt(15)
	v_fma_f32 v150, -v152, v128, v152
	v_add_f32_e32 v152, v150, v136
	v_mul_f32_e32 v170, v152, v144
	ds_read_u16_d16_hi v127, v121 offset:3600
	ds_read_u16_d16_hi v135, v122 offset:3600
	ds_read_u16_d16_hi v143, v123 offset:3600
	s_waitcnt lgkmcnt(15)
	v_fma_f32 v150, -v152, v129, v152
	v_add_f32_e32 v152, v150, v137
	v_mul_f32_e32 v171, v152, v145
	ds_read_u16_d16_hi v128, v121 offset:4000
	ds_read_u16_d16_hi v136, v122 offset:4000
	ds_read_u16_d16_hi v144, v123 offset:4000
	v_cvt_pk_bf16_f32 v151, v170, v171
	ds_write_b32 v124, v151 offset:800
	s_waitcnt lgkmcnt(15)
	v_fma_f32 v150, -v152, v130, v152
	v_add_f32_e32 v152, v150, v138
	v_mul_f32_e32 v170, v152, v146
	ds_read_u16_d16_hi v129, v121 offset:4400
	ds_read_u16_d16_hi v137, v122 offset:4400
	ds_read_u16_d16_hi v145, v123 offset:4400
	s_waitcnt lgkmcnt(15)
	v_fma_f32 v150, -v152, v131, v152
	v_add_f32_e32 v152, v150, v139
	v_mul_f32_e32 v171, v152, v147
	ds_read_u16_d16_hi v130, v121 offset:4800
	ds_read_u16_d16_hi v138, v122 offset:4800
	ds_read_u16_d16_hi v146, v123 offset:4800
	v_cvt_pk_bf16_f32 v151, v170, v171
	ds_write_b32 v124, v151 offset:1600
	s_waitcnt lgkmcnt(15)
	v_fma_f32 v150, -v152, v132, v152
	v_add_f32_e32 v152, v150, v140
	v_mul_f32_e32 v170, v152, v148
	ds_read_u16_d16_hi v131, v121 offset:5200
	ds_read_u16_d16_hi v139, v122 offset:5200
	ds_read_u16_d16_hi v147, v123 offset:5200
	s_waitcnt lgkmcnt(15)
	v_fma_f32 v150, -v152, v133, v152
	v_add_f32_e32 v152, v150, v141
	v_mul_f32_e32 v171, v152, v149
	ds_read_u16_d16_hi v132, v121 offset:5600
	ds_read_u16_d16_hi v140, v122 offset:5600
	ds_read_u16_d16_hi v148, v123 offset:5600
	v_cvt_pk_bf16_f32 v151, v170, v171
	ds_write_b32 v124, v151 offset:2400
	s_waitcnt lgkmcnt(15)
	v_fma_f32 v150, -v152, v126, v152
	v_add_f32_e32 v152, v150, v134
	v_mul_f32_e32 v170, v152, v142
	ds_read_u16_d16_hi v133, v121 offset:6000
	ds_read_u16_d16_hi v141, v122 offset:6000
	ds_read_u16_d16_hi v149, v123 offset:6000
	s_waitcnt lgkmcnt(15)
	v_fma_f32 v150, -v152, v127, v152
	v_add_f32_e32 v152, v150, v135
	v_mul_f32_e32 v171, v152, v143
	ds_read_u16_d16_hi v126, v121 offset:6400
	ds_read_u16_d16_hi v134, v122 offset:6400
	ds_read_u16_d16_hi v142, v123 offset:6400
	v_cvt_pk_bf16_f32 v151, v170, v171
	ds_write_b32 v124, v151 offset:3200
	s_waitcnt lgkmcnt(15)
	v_fma_f32 v150, -v152, v128, v152
	v_add_f32_e32 v152, v150, v136
	v_mul_f32_e32 v170, v152, v144
	ds_read_u16_d16_hi v127, v121 offset:6800
	ds_read_u16_d16_hi v135, v122 offset:6800
	ds_read_u16_d16_hi v143, v123 offset:6800
	s_waitcnt lgkmcnt(15)
	v_fma_f32 v150, -v152, v129, v152
	v_add_f32_e32 v152, v150, v137
	v_mul_f32_e32 v171, v152, v145
	ds_read_u16_d16_hi v128, v121 offset:7200
	ds_read_u16_d16_hi v136, v122 offset:7200
	ds_read_u16_d16_hi v144, v123 offset:7200
	v_cvt_pk_bf16_f32 v151, v170, v171
	ds_write_b32 v124, v151 offset:4000
	s_waitcnt lgkmcnt(15)
	v_fma_f32 v150, -v152, v130, v152
	v_add_f32_e32 v152, v150, v138
	v_mul_f32_e32 v170, v152, v146
	ds_read_u16_d16_hi v129, v121 offset:7600
	ds_read_u16_d16_hi v137, v122 offset:7600
	ds_read_u16_d16_hi v145, v123 offset:7600
	s_waitcnt lgkmcnt(15)
	v_fma_f32 v150, -v152, v131, v152
	v_add_f32_e32 v152, v150, v139
	v_mul_f32_e32 v171, v152, v147
	ds_read_u16_d16_hi v130, v121 offset:8000
	ds_read_u16_d16_hi v138, v122 offset:8000
	ds_read_u16_d16_hi v146, v123 offset:8000
	v_cvt_pk_bf16_f32 v151, v170, v171
	ds_write_b32 v124, v151 offset:4800
	s_waitcnt lgkmcnt(15)
; #define LAS __attribute__((address_space(3)))
; DI unsigned pk2(float a, float b) { f32x2 v = {a, b}; bf2_t r = __builtin_convertvector(v, bf2_t); return __builtin_bit_cast(unsigned, r); }
; DI void phase_rglru(const Params& p, unsigned char* shm) {
;     ...
;             if (tid < 192) {
; #pragma unroll 8
;                 for (int r = 0; r < 64; ++r) {
;                     const float om = __uint_as_float((unsigned)*(const LAS bf16_t*)(lds + LAo + r * TR + tid * 2) << 16);
;                     const float bt = __uint_as_float((unsigned)*(const LAS bf16_t*)(lds + BTo + r * TR + tid * 2) << 16);
;                     const float g = __uint_as_float((unsigned)*(const LAS bf16_t*)(lds + GT + r * TR + tid * 2) << 16);
;                     hst = (hst - om * hst) + bt;
;                     *(LAS bf16_t*)(lds + GT + r * TR + tid * 2) = (bf16_t)(pk2(hst * g, 0.f) & 0xffffu);
;                 }
	v_fma_f32 v150, -v152, v132, v152
	v_add_f32_e32 v152, v150, v140
	v_mul_f32_e32 v170, v152, v148
	ds_read_u16_d16_hi v131, v121 offset:8400
	ds_read_u16_d16_hi v139, v122 offset:8400
	ds_read_u16_d16_hi v147, v123 offset:8400
	s_waitcnt lgkmcnt(15)
	v_fma_f32 v150, -v152, v133, v152
	v_add_f32_e32 v152, v150, v141
	v_mul_f32_e32 v171, v152, v149
	ds_read_u16_d16_hi v132, v121 offset:8800
	ds_read_u16_d16_hi v140, v122 offset:8800
	ds_read_u16_d16_hi v148, v123 offset:8800
	v_cvt_pk_bf16_f32 v151, v170, v171
	ds_write_b32 v124, v151 offset:5600
	s_waitcnt lgkmcnt(15)
	v_fma_f32 v150, -v152, v126, v152
	v_add_f32_e32 v152, v150, v134
	v_mul_f32_e32 v170, v152, v142
	ds_read_u16_d16_hi v133, v121 offset:9200
	ds_read_u16_d16_hi v141, v122 offset:9200
	ds_read_u16_d16_hi v149, v123 offset:9200
	s_waitcnt lgkmcnt(15)
	v_fma_f32 v150, -v152, v127, v152
	v_add_f32_e32 v152, v150, v135
	v_mul_f32_e32 v171, v152, v143
	ds_read_u16_d16_hi v126, v121 offset:9600
	ds_read_u16_d16_hi v134, v122 offset:9600
	ds_read_u16_d16_hi v142, v123 offset:9600
	v_cvt_pk_bf16_f32 v151, v170, v171
	ds_write_b32 v124, v151 offset:6400
	s_waitcnt lgkmcnt(15)
	v_fma_f32 v150, -v152, v128, v152
	v_add_f32_e32 v152, v150, v136
	v_mul_f32_e32 v170, v152, v144
	ds_read_u16_d16_hi v127, v121 offset:10000
	ds_read_u16_d16_hi v135, v122 offset:10000
	ds_read_u16_d16_hi v143, v123 offset:10000
	s_waitcnt lgkmcnt(15)
	v_fma_f32 v150, -v152, v129, v152
	v_add_f32_e32 v152, v150, v137
	v_mul_f32_e32 v171, v152, v145
	ds_read_u16_d16_hi v128, v121 offset:10400
	ds_read_u16_d16_hi v136, v122 offset:10400
	ds_read_u16_d16_hi v144, v123 offset:10400
	v_cvt_pk_bf16_f32 v151, v170, v171
	ds_write_b32 v124, v151 offset:7200
	s_waitcnt lgkmcnt(15)
	v_fma_f32 v150, -v152, v130, v152
	v_add_f32_e32 v152, v150, v138
	v_mul_f32_e32 v170, v152, v146
	ds_read_u16_d16_hi v129, v121 offset:10800
	ds_read_u16_d16_hi v137, v122 offset:10800
	ds_read_u16_d16_hi v145, v123 offset:10800
	s_waitcnt lgkmcnt(15)
	v_fma_f32 v150, -v152, v131, v152
	v_add_f32_e32 v152, v150, v139
	v_mul_f32_e32 v171, v152, v147
	ds_read_u16_d16_hi v130, v121 offset:11200
	ds_read_u16_d16_hi v138, v122 offset:11200
	ds_read_u16_d16_hi v146, v123 offset:11200
	v_cvt_pk_bf16_f32 v151, v170, v171
	ds_write_b32 v124, v151 offset:8000
	s_waitcnt lgkmcnt(15)
	v_fma_f32 v150, -v152, v132, v152
	v_add_f32_e32 v152, v150, v140
	v_mul_f32_e32 v170, v152, v148
	ds_read_u16_d16_hi v131, v121 offset:11600
	ds_read_u16_d16_hi v139, v122 offset:11600
	ds_read_u16_d16_hi v147, v123 offset:11600
	s_waitcnt lgkmcnt(15)
	v_fma_f32 v150, -v152, v133, v152
	v_add_f32_e32 v152, v150, v141
	v_mul_f32_e32 v171, v152, v149
	ds_read_u16_d16_hi v132, v121 offset:12000
	ds_read_u16_d16_hi v140, v122 offset:12000
	ds_read_u16_d16_hi v148, v123 offset:12000
	v_cvt_pk_bf16_f32 v151, v170, v171
	ds_write_b32 v124, v151 offset:8800
	s_waitcnt lgkmcnt(15)
	v_fma_f32 v150, -v152, v126, v152
	v_add_f32_e32 v152, v150, v134
	v_mul_f32_e32 v170, v152, v142
	ds_read_u16_d16_hi v133, v121 offset:12400
	ds_read_u16_d16_hi v141, v122 offset:12400
	ds_read_u16_d16_hi v149, v123 offset:12400
	s_waitcnt lgkmcnt(15)
	v_fma_f32 v150, -v152, v127, v152
	v_add_f32_e32 v152, v150, v135
	v_mul_f32_e32 v171, v152, v143
	ds_read_u16_d16_hi v126, v121 offset:12800
	ds_read_u16_d16_hi v134, v122 offset:12800
	ds_read_u16_d16_hi v142, v123 offset:12800
	v_cvt_pk_bf16_f32 v151, v170, v171
	ds_write_b32 v124, v151 offset:9600
	s_waitcnt lgkmcnt(15)
	v_fma_f32 v150, -v152, v128, v152
	v_add_f32_e32 v152, v150, v136
	v_mul_f32_e32 v170, v152, v144
	ds_read_u16_d16_hi v127, v121 offset:13200
	ds_read_u16_d16_hi v135, v122 offset:13200
	ds_read_u16_d16_hi v143, v123 offset:13200
	s_waitcnt lgkmcnt(15)
	v_fma_f32 v150, -v152, v129, v152
	v_add_f32_e32 v152, v150, v137
	v_mul_f32_e32 v171, v152, v145
	ds_read_u16_d16_hi v128, v121 offset:13600
	ds_read_u16_d16_hi v136, v122 offset:13600
	ds_read_u16_d16_hi v144, v123 offset:13600
	v_cvt_pk_bf16_f32 v151, v170, v171
	ds_write_b32 v124, v151 offset:10400
	s_waitcnt lgkmcnt(15)
	v_fma_f32 v150, -v152, v130, v152
	v_add_f32_e32 v152, v150, v138
	v_mul_f32_e32 v170, v152, v146
	ds_read_u16_d16_hi v129, v121 offset:14000
	ds_read_u16_d16_hi v137, v122 offset:14000
	ds_read_u16_d16_hi v145, v123 offset:14000
	s_waitcnt lgkmcnt(15)
	v_fma_f32 v150, -v152, v131, v152
	v_add_f32_e32 v152, v150, v139
	v_mul_f32_e32 v171, v152, v147
	ds_read_u16_d16_hi v130, v121 offset:14400
	ds_read_u16_d16_hi v138, v122 offset:14400
	ds_read_u16_d16_hi v146, v123 offset:14400
	v_cvt_pk_bf16_f32 v151, v170, v171
	ds_write_b32 v124, v151 offset:11200
	s_waitcnt lgkmcnt(15)
	v_fma_f32 v150, -v152, v132, v152
	v_add_f32_e32 v152, v150, v140
	v_mul_f32_e32 v170, v152, v148
	ds_read_u16_d16_hi v131, v121 offset:14800
	ds_read_u16_d16_hi v139, v122 offset:14800
	ds_read_u16_d16_hi v147, v123 offset:14800
	s_waitcnt lgkmcnt(15)
	v_fma_f32 v150, -v152, v133, v152
	v_add_f32_e32 v152, v150, v141
	v_mul_f32_e32 v171, v152, v149
	ds_read_u16_d16_hi v132, v121 offset:15200
	ds_read_u16_d16_hi v140, v122 offset:15200
	ds_read_u16_d16_hi v148, v123 offset:15200
	v_cvt_pk_bf16_f32 v151, v170, v171
	ds_write_b32 v124, v151 offset:12000
	s_waitcnt lgkmcnt(15)
	v_fma_f32 v150, -v152, v126, v152
	v_add_f32_e32 v152, v150, v134
	v_mul_f32_e32 v170, v152, v142
	ds_read_u16_d16_hi v133, v121 offset:15600
	ds_read_u16_d16_hi v141, v122 offset:15600
	ds_read_u16_d16_hi v149, v123 offset:15600
	s_waitcnt lgkmcnt(15)
	v_fma_f32 v150, -v152, v127, v152
	v_add_f32_e32 v152, v150, v135
	v_mul_f32_e32 v171, v152, v143
	ds_read_u16_d16_hi v126, v121 offset:16000
	ds_read_u16_d16_hi v134, v122 offset:16000
	ds_read_u16_d16_hi v142, v123 offset:16000
	v_cvt_pk_bf16_f32 v151, v170, v171
	ds_write_b32 v124, v151 offset:12800
	s_waitcnt lgkmcnt(15)
; #define LAS __attribute__((address_space(3)))
; DI unsigned pk2(float a, float b) { f32x2 v = {a, b}; bf2_t r = __builtin_convertvector(v, bf2_t); return __builtin_bit_cast(unsigned, r); }
; DI void phase_rglru(const Params& p, unsigned char* shm) {
;     ...
;             if (tid < 192) {
; #pragma unroll 8
;                 for (int r = 0; r < 64; ++r) {
;                     const float om = __uint_as_float((unsigned)*(const LAS bf16_t*)(lds + LAo + r * TR + tid * 2) << 16);
;                     const float bt = __uint_as_float((unsigned)*(const LAS bf16_t*)(lds + BTo + r * TR + tid * 2) << 16);
;                     const float g = __uint_as_float((unsigned)*(const LAS bf16_t*)(lds + GT + r * TR + tid * 2) << 16);
;                     hst = (hst - om * hst) + bt;
;                     *(LAS bf16_t*)(lds + GT + r * TR + tid * 2) = (bf16_t)(pk2(hst * g, 0.f) & 0xffffu);
;                 }
	v_fma_f32 v150, -v152, v128, v152
	v_add_f32_e32 v152, v150, v136
	v_mul_f32_e32 v170, v152, v144
	ds_read_u16_d16_hi v127, v121 offset:16400
	ds_read_u16_d16_hi v135, v122 offset:16400
	ds_read_u16_d16_hi v143, v123 offset:16400
	s_waitcnt lgkmcnt(15)
	v_fma_f32 v150, -v152, v129, v152
	v_add_f32_e32 v152, v150, v137
	v_mul_f32_e32 v171, v152, v145
	ds_read_u16_d16_hi v128, v121 offset:16800
	ds_read_u16_d16_hi v136, v122 offset:16800
	ds_read_u16_d16_hi v144, v123 offset:16800
	v_cvt_pk_bf16_f32 v151, v170, v171
	ds_write_b32 v124, v151 offset:13600
	s_waitcnt lgkmcnt(15)
	v_fma_f32 v150, -v152, v130, v152
	v_add_f32_e32 v152, v150, v138
	v_mul_f32_e32 v170, v152, v146
	ds_read_u16_d16_hi v129, v121 offset:17200
	ds_read_u16_d16_hi v137, v122 offset:17200
	ds_read_u16_d16_hi v145, v123 offset:17200
	s_waitcnt lgkmcnt(15)
	v_fma_f32 v150, -v152, v131, v152
	v_add_f32_e32 v152, v150, v139
	v_mul_f32_e32 v171, v152, v147
	ds_read_u16_d16_hi v130, v121 offset:17600
	ds_read_u16_d16_hi v138, v122 offset:17600
	ds_read_u16_d16_hi v146, v123 offset:17600
	v_cvt_pk_bf16_f32 v151, v170, v171
	ds_write_b32 v124, v151 offset:14400
	s_waitcnt lgkmcnt(15)
	v_fma_f32 v150, -v152, v132, v152
	v_add_f32_e32 v152, v150, v140
	v_mul_f32_e32 v170, v152, v148
	ds_read_u16_d16_hi v131, v121 offset:18000
	ds_read_u16_d16_hi v139, v122 offset:18000
	ds_read_u16_d16_hi v147, v123 offset:18000
	s_waitcnt lgkmcnt(15)
	v_fma_f32 v150, -v152, v133, v152
	v_add_f32_e32 v152, v150, v141
	v_mul_f32_e32 v171, v152, v149
	ds_read_u16_d16_hi v132, v121 offset:18400
	ds_read_u16_d16_hi v140, v122 offset:18400
	ds_read_u16_d16_hi v148, v123 offset:18400
	v_cvt_pk_bf16_f32 v151, v170, v171
	ds_write_b32 v124, v151 offset:15200
	s_waitcnt lgkmcnt(15)
	v_fma_f32 v150, -v152, v126, v152
	v_add_f32_e32 v152, v150, v134
	v_mul_f32_e32 v170, v152, v142
	ds_read_u16_d16_hi v133, v121 offset:18800
	ds_read_u16_d16_hi v141, v122 offset:18800
	ds_read_u16_d16_hi v149, v123 offset:18800
	s_waitcnt lgkmcnt(15)
	v_fma_f32 v150, -v152, v127, v152
	v_add_f32_e32 v152, v150, v135
	v_mul_f32_e32 v171, v152, v143
	ds_read_u16_d16_hi v126, v121 offset:19200
	ds_read_u16_d16_hi v134, v122 offset:19200
	ds_read_u16_d16_hi v142, v123 offset:19200
	v_cvt_pk_bf16_f32 v151, v170, v171
	ds_write_b32 v124, v151 offset:16000
	s_waitcnt lgkmcnt(15)
	v_fma_f32 v150, -v152, v128, v152
	v_add_f32_e32 v152, v150, v136
	v_mul_f32_e32 v170, v152, v144
	ds_read_u16_d16_hi v127, v121 offset:19600
	ds_read_u16_d16_hi v135, v122 offset:19600
	ds_read_u16_d16_hi v143, v123 offset:19600
	s_waitcnt lgkmcnt(15)
	v_fma_f32 v150, -v152, v129, v152
	v_add_f32_e32 v152, v150, v137
	v_mul_f32_e32 v171, v152, v145
	ds_read_u16_d16_hi v128, v121 offset:20000
	ds_read_u16_d16_hi v136, v122 offset:20000
	ds_read_u16_d16_hi v144, v123 offset:20000
	v_cvt_pk_bf16_f32 v151, v170, v171
	ds_write_b32 v124, v151 offset:16800
	s_waitcnt lgkmcnt(15)
	v_fma_f32 v150, -v152, v130, v152
	v_add_f32_e32 v152, v150, v138
	v_mul_f32_e32 v170, v152, v146
	ds_read_u16_d16_hi v129, v121 offset:20400
	ds_read_u16_d16_hi v137, v122 offset:20400
	ds_read_u16_d16_hi v145, v123 offset:20400
	s_waitcnt lgkmcnt(15)
	v_fma_f32 v150, -v152, v131, v152
	v_add_f32_e32 v152, v150, v139
	v_mul_f32_e32 v171, v152, v147
	ds_read_u16_d16_hi v130, v121 offset:20800
	ds_read_u16_d16_hi v138, v122 offset:20800
	ds_read_u16_d16_hi v146, v123 offset:20800
	v_cvt_pk_bf16_f32 v151, v170, v171
	ds_write_b32 v124, v151 offset:17600
	s_waitcnt lgkmcnt(15)
	v_fma_f32 v150, -v152, v132, v152
	v_add_f32_e32 v152, v150, v140
	v_mul_f32_e32 v170, v152, v148
	ds_read_u16_d16_hi v131, v121 offset:21200
	ds_read_u16_d16_hi v139, v122 offset:21200
	ds_read_u16_d16_hi v147, v123 offset:21200
	s_waitcnt lgkmcnt(15)
; #define LAS __attribute__((address_space(3)))
; DI unsigned pk2(float a, float b) { f32x2 v = {a, b}; bf2_t r = __builtin_convertvector(v, bf2_t); return __builtin_bit_cast(unsigned, r); }
; DI void phase_rglru(const Params& p, unsigned char* shm) {
;     ...
;             if (tid < 192) {
; #pragma unroll 8
;                 for (int r = 0; r < 64; ++r) {
;                     const float om = __uint_as_float((unsigned)*(const LAS bf16_t*)(lds + LAo + r * TR + tid * 2) << 16);
;                     const float bt = __uint_as_float((unsigned)*(const LAS bf16_t*)(lds + BTo + r * TR + tid * 2) << 16);
;                     const float g = __uint_as_float((unsigned)*(const LAS bf16_t*)(lds + GT + r * TR + tid * 2) << 16);
;                     hst = (hst - om * hst) + bt;
;                     *(LAS bf16_t*)(lds + GT + r * TR + tid * 2) = (bf16_t)(pk2(hst * g, 0.f) & 0xffffu);
;                 }
	v_fma_f32 v150, -v152, v133, v152
	v_add_f32_e32 v152, v150, v141
	v_mul_f32_e32 v171, v152, v149
	ds_read_u16_d16_hi v132, v121 offset:21600
	ds_read_u16_d16_hi v140, v122 offset:21600
	ds_read_u16_d16_hi v148, v123 offset:21600
	v_cvt_pk_bf16_f32 v151, v170, v171
	ds_write_b32 v124, v151 offset:18400
	s_waitcnt lgkmcnt(15)
	v_fma_f32 v150, -v152, v126, v152
	v_add_f32_e32 v152, v150, v134
	v_mul_f32_e32 v170, v152, v142
	ds_read_u16_d16_hi v133, v121 offset:22000
	ds_read_u16_d16_hi v141, v122 offset:22000
	ds_read_u16_d16_hi v149, v123 offset:22000
	s_waitcnt lgkmcnt(15)
	v_fma_f32 v150, -v152, v127, v152
	v_add_f32_e32 v152, v150, v135
	v_mul_f32_e32 v171, v152, v143
	ds_read_u16_d16_hi v126, v121 offset:22400
	ds_read_u16_d16_hi v134, v122 offset:22400
	ds_read_u16_d16_hi v142, v123 offset:22400
	v_cvt_pk_bf16_f32 v151, v170, v171
	ds_write_b32 v124, v151 offset:19200
	s_waitcnt lgkmcnt(15)
	v_fma_f32 v150, -v152, v128, v152
	v_add_f32_e32 v152, v150, v136
	v_mul_f32_e32 v170, v152, v144
	ds_read_u16_d16_hi v127, v121 offset:22800
	ds_read_u16_d16_hi v135, v122 offset:22800
	ds_read_u16_d16_hi v143, v123 offset:22800
	s_waitcnt lgkmcnt(15)
	v_fma_f32 v150, -v152, v129, v152
	v_add_f32_e32 v152, v150, v137
	v_mul_f32_e32 v171, v152, v145
	ds_read_u16_d16_hi v128, v121 offset:23200
	ds_read_u16_d16_hi v136, v122 offset:23200
	ds_read_u16_d16_hi v144, v123 offset:23200
	v_cvt_pk_bf16_f32 v151, v170, v171
	ds_write_b32 v124, v151 offset:20000
	s_waitcnt lgkmcnt(15)
	v_fma_f32 v150, -v152, v130, v152
	v_add_f32_e32 v152, v150, v138
	v_mul_f32_e32 v170, v152, v146
	ds_read_u16_d16_hi v129, v121 offset:23600
	ds_read_u16_d16_hi v137, v122 offset:23600
	ds_read_u16_d16_hi v145, v123 offset:23600
	s_waitcnt lgkmcnt(15)
	v_fma_f32 v150, -v152, v131, v152
	v_add_f32_e32 v152, v150, v139
	v_mul_f32_e32 v171, v152, v147
	ds_read_u16_d16_hi v130, v121 offset:24000
	ds_read_u16_d16_hi v138, v122 offset:24000
	ds_read_u16_d16_hi v146, v123 offset:24000
	v_cvt_pk_bf16_f32 v151, v170, v171
	ds_write_b32 v124, v151 offset:20800
	s_waitcnt lgkmcnt(15)
	v_fma_f32 v150, -v152, v132, v152
	v_add_f32_e32 v152, v150, v140
	v_mul_f32_e32 v170, v152, v148
	ds_read_u16_d16_hi v131, v121 offset:24400
	ds_read_u16_d16_hi v139, v122 offset:24400
	ds_read_u16_d16_hi v147, v123 offset:24400
	s_waitcnt lgkmcnt(15)
	v_fma_f32 v150, -v152, v133, v152
	v_add_f32_e32 v152, v150, v141
	v_mul_f32_e32 v171, v152, v149
	ds_read_u16_d16_hi v132, v121 offset:24800
	ds_read_u16_d16_hi v140, v122 offset:24800
	ds_read_u16_d16_hi v148, v123 offset:24800
	v_cvt_pk_bf16_f32 v151, v170, v171
	ds_write_b32 v124, v151 offset:21600
	s_waitcnt lgkmcnt(15)
	v_fma_f32 v150, -v152, v126, v152
	v_add_f32_e32 v152, v150, v134
	v_mul_f32_e32 v170, v152, v142
	ds_read_u16_d16_hi v133, v121 offset:25200
	ds_read_u16_d16_hi v141, v122 offset:25200
	ds_read_u16_d16_hi v149, v123 offset:25200
	s_waitcnt lgkmcnt(15)
	v_fma_f32 v150, -v152, v127, v152
	v_add_f32_e32 v152, v150, v135
	v_mul_f32_e32 v171, v152, v143
	v_cvt_pk_bf16_f32 v151, v170, v171
	ds_write_b32 v124, v151 offset:22400
	s_waitcnt lgkmcnt(15)
	v_fma_f32 v150, -v152, v128, v152
	v_add_f32_e32 v152, v150, v136
	v_mul_f32_e32 v170, v152, v144
	s_waitcnt lgkmcnt(15)
	v_fma_f32 v150, -v152, v129, v152
	v_add_f32_e32 v152, v150, v137
	v_mul_f32_e32 v171, v152, v145
	v_cvt_pk_bf16_f32 v151, v170, v171
	ds_write_b32 v124, v151 offset:23200
	s_waitcnt lgkmcnt(13)
	v_fma_f32 v150, -v152, v130, v152
	v_add_f32_e32 v152, v150, v138
	v_mul_f32_e32 v170, v152, v146
	s_waitcnt lgkmcnt(9)
	v_fma_f32 v150, -v152, v131, v152
	v_add_f32_e32 v152, v150, v139
	v_mul_f32_e32 v171, v152, v147
	v_cvt_pk_bf16_f32 v151, v170, v171
	ds_write_b32 v124, v151 offset:24000
	s_waitcnt lgkmcnt(7)
	v_fma_f32 v150, -v152, v132, v152
	v_add_f32_e32 v152, v150, v140
	v_mul_f32_e32 v170, v152, v148
	s_waitcnt lgkmcnt(3)
	v_fma_f32 v150, -v152, v133, v152
	v_add_f32_e32 v152, v150, v141
	v_mul_f32_e32 v171, v152, v149
	v_cvt_pk_bf16_f32 v151, v170, v171
	ds_write_b32 v124, v151 offset:24800
	s_branch .LBB0_842
